# attention: priority sense flipped, MFMA sections (PV, next QK, issue) at prio 1 and softmax VALU at prio 0
# speedup vs baseline: 1.0045x; 1.0045x over previous
; #define LAS __attribute__((address_space(3)))
; DI unsigned pk2(float lo, float hi) { f32x2 v = {lo, hi}; bf2_t r = __builtin_convertvector(v, bf2_t); return __builtin_bit_cast(unsigned, r); }
; DI void phase_attn(const Params& p, int l, LAS char* lds) {
;     ...
;             __builtin_amdgcn_s_setprio(1);
;             float mx = s0[0];
; #pragma unroll
;             for (int r = 1; r < 16; ++r) mx = fmaxf(mx, s0[r]);
; #pragma unroll
;             for (int r = 0; r < 16; ++r) mx = fmaxf(mx, s1[r]);
;             {
;                 const auto rr = __builtin_amdgcn_permlane32_swap(__float_as_uint(mx), __float_as_uint(mx), false, false);
;                 mx = fmaxf(__uint_as_float(rr[0]), __uint_as_float(rr[1]));
;             }
;             float m_new = m_run;
;             if (__builtin_amdgcn_ballot_w64(mx - m_run > 8.f) != 0ull) {
;                 m_new = fmaxf(m_run, mx);
;                 const float alpha = __builtin_amdgcn_exp2f(m_run - m_new);
;                 m_run = m_new;
;                 l_run *= alpha;
; #pragma unroll
;                 for (int r = 0; r < 16; ++r) { o0[r] *= alpha; o1[r] *= alpha; }
;             }
;             float ps = 0.f;
; #pragma unroll
;             for (int r = 0; r < 16; ++r) { s0[r] = __builtin_amdgcn_exp2f(s0[r] - m_new); s1[r] = __builtin_amdgcn_exp2f(s1[r] - m_new); ps += s0[r] + s1[r]; }
;             l_run += ps;
;             bf16x8 pf[2][2];
; #pragma unroll
;             for (int s2 = 0; s2 < 2; ++s2) {
;                 u32x4 a, c2;
; #pragma unroll
;                 for (int e = 0; e < 4; ++e) { a[e] = pk2(s0[8 * s2 + 2 * e], s0[8 * s2 + 2 * e + 1]); c2[e] = pk2(s1[8 * s2 + 2 * e], s1[8 * s2 + 2 * e + 1]); }
;                 pf[0][s2] = __builtin_bit_cast(bf16x8, a); pf[1][s2] = __builtin_bit_cast(bf16x8, c2);
;             }
;             LAS char* vs = st + 12288;
;             __builtin_amdgcn_s_setprio(0);
; #pragma unroll
;             for (int tl = 0; tl < 2; ++tl)
; #pragma unroll
;                 for (int s2 = 0; s2 < 2; ++s2) {
;                     const int c = 4 * tl + 2 * s2;
;                     const int p0 = ((c ^ vsw) << 4) + 8 * hh, p1 = (((c + 1) ^ vsw) << 4) + 8 * hh;
;                     const s16x4 a0 = *(LAS s16x4*)(vs + qi * 128 + p0), a1 = *(LAS s16x4*)(vs + qi * 128 + p1);
.LBB0_290:
	s_or_b64 exec, exec, s[52:53]
	s_setprio 0
	s_nop 4
	v_max_f32_e32 v1, v34, v35
	v_max3_f32 v1, v1, v36, v37
	v_max3_f32 v1, v1, v38, v39
	v_max3_f32 v1, v1, v40, v41
	v_max3_f32 v1, v1, v42, v43
	v_max3_f32 v1, v1, v44, v45
	v_max3_f32 v1, v1, v46, v47
	v_max3_f32 v1, v1, v48, v49
	v_max3_f32 v1, v1, v50, v51
	v_max3_f32 v1, v1, v52, v53
	v_max3_f32 v1, v1, v54, v55
	v_max3_f32 v1, v1, v56, v57
	v_max3_f32 v1, v1, v58, v59
	v_max3_f32 v1, v1, v60, v61
	v_max3_f32 v1, v1, v62, v63
	v_max3_f32 v1, v1, v64, v65
	v_mov_b32_e32 v183, v1
	s_nop 1
	v_permlane32_swap_b32_e32 v1, v183
	v_max_f32_e32 v1, v1, v183
	v_sub_f32_e32 v183, v1, v182
	s_mov_b32 s4, 0x41000000
	v_cmp_lt_f32_e32 vcc, s4, v183
	s_cbranch_vccz .LBB0_292
	v_max_f32_e32 v1, v1, v1
	v_max_f32_e32 v183, v182, v182
	v_max_f32_e32 v1, v183, v1
	v_sub_f32_e32 v182, v182, v1
	v_exp_f32_e32 v182, v182
	s_nop 0
	v_pk_mul_f32 v[32:33], v[32:33], v[182:183] op_sel_hi:[1,0]
	v_pk_mul_f32 v[30:31], v[30:31], v[182:183] op_sel_hi:[1,0]
	v_pk_mul_f32 v[28:29], v[28:29], v[182:183] op_sel_hi:[1,0]
	v_pk_mul_f32 v[26:27], v[26:27], v[182:183] op_sel_hi:[1,0]
	v_pk_mul_f32 v[24:25], v[24:25], v[182:183] op_sel_hi:[1,0]
	v_pk_mul_f32 v[22:23], v[22:23], v[182:183] op_sel_hi:[1,0]
	v_pk_mul_f32 v[20:21], v[20:21], v[182:183] op_sel_hi:[1,0]
	v_pk_mul_f32 v[18:19], v[18:19], v[182:183] op_sel_hi:[1,0]
	v_pk_mul_f32 v[16:17], v[16:17], v[182:183] op_sel_hi:[1,0]
	v_pk_mul_f32 v[14:15], v[14:15], v[182:183] op_sel_hi:[1,0]
	v_pk_mul_f32 v[12:13], v[12:13], v[182:183] op_sel_hi:[1,0]
	v_pk_mul_f32 v[10:11], v[10:11], v[182:183] op_sel_hi:[1,0]
	v_pk_mul_f32 v[8:9], v[8:9], v[182:183] op_sel_hi:[1,0]
	v_pk_mul_f32 v[6:7], v[6:7], v[182:183] op_sel_hi:[1,0]
	v_pk_mul_f32 v[4:5], v[4:5], v[182:183] op_sel_hi:[1,0]
	v_pk_mul_f32 v[2:3], v[2:3], v[182:183] op_sel_hi:[1,0]
	v_mul_f32_e32 v181, v181, v182
	v_mov_b32_e32 v182, v1
.LBB0_292:
	v_sub_f32_e32 v34, v34, v182
	v_sub_f32_e32 v35, v35, v182
	v_sub_f32_e32 v36, v36, v182
	v_sub_f32_e32 v37, v37, v182
	v_sub_f32_e32 v38, v38, v182
	v_sub_f32_e32 v39, v39, v182
	v_sub_f32_e32 v40, v40, v182
	v_sub_f32_e32 v41, v41, v182
	v_sub_f32_e32 v42, v42, v182
	v_sub_f32_e32 v43, v43, v182
	v_sub_f32_e32 v44, v44, v182
	v_sub_f32_e32 v45, v45, v182
	v_sub_f32_e32 v46, v46, v182
	v_sub_f32_e32 v47, v47, v182
	v_sub_f32_e32 v48, v48, v182
	v_sub_f32_e32 v49, v49, v182
	v_sub_f32_e32 v50, v50, v182
	v_sub_f32_e32 v51, v51, v182
	v_sub_f32_e32 v52, v52, v182
	v_sub_f32_e32 v53, v53, v182
	v_sub_f32_e32 v54, v54, v182
	v_sub_f32_e32 v55, v55, v182
	v_sub_f32_e32 v56, v56, v182
	v_sub_f32_e32 v57, v57, v182
	v_sub_f32_e32 v58, v58, v182
	v_sub_f32_e32 v59, v59, v182
	v_sub_f32_e32 v60, v60, v182
	v_sub_f32_e32 v61, v61, v182
	v_sub_f32_e32 v62, v62, v182
	v_sub_f32_e32 v63, v63, v182
	v_sub_f32_e32 v64, v64, v182
	v_sub_f32_e32 v65, v65, v182
	v_exp_f32_e32 v34, v34
	v_exp_f32_e32 v35, v35
	v_exp_f32_e32 v36, v36
	v_exp_f32_e32 v37, v37
	v_exp_f32_e32 v38, v38
	v_exp_f32_e32 v39, v39
	v_exp_f32_e32 v40, v40
	v_exp_f32_e32 v41, v41
	v_exp_f32_e32 v42, v42
	v_exp_f32_e32 v43, v43
	v_exp_f32_e32 v44, v44
	v_exp_f32_e32 v45, v45
	v_exp_f32_e32 v46, v46
	v_exp_f32_e32 v47, v47
	v_exp_f32_e32 v48, v48
	v_exp_f32_e32 v49, v49
	v_exp_f32_e32 v50, v50
	v_exp_f32_e32 v51, v51
	v_exp_f32_e32 v52, v52
	v_exp_f32_e32 v53, v53
	v_exp_f32_e32 v54, v54
	v_exp_f32_e32 v55, v55
	v_exp_f32_e32 v56, v56
	v_exp_f32_e32 v57, v57
	v_exp_f32_e32 v58, v58
	v_exp_f32_e32 v59, v59
	v_exp_f32_e32 v60, v60
	v_exp_f32_e32 v61, v61
	v_exp_f32_e32 v62, v62
	v_exp_f32_e32 v63, v63
	v_exp_f32_e32 v64, v64
	v_exp_f32_e32 v65, v65
	v_add_f32_e32 v184, v34, v35
	v_add_f32_e32 v185, v50, v51
	v_add_f32_e32 v186, v36, v37
	v_add_f32_e32 v187, v52, v53
	v_add_f32_e32 v184, v184, v38
	v_add_f32_e32 v185, v185, v54
	v_add_f32_e32 v186, v186, v39
	v_add_f32_e32 v187, v187, v55
	v_add_f32_e32 v184, v184, v40
	v_add_f32_e32 v185, v185, v56
	v_add_f32_e32 v186, v186, v41
	v_add_f32_e32 v187, v187, v57
	v_add_f32_e32 v184, v184, v42
	v_add_f32_e32 v185, v185, v58
	v_add_f32_e32 v186, v186, v43
	v_add_f32_e32 v187, v187, v59
	v_add_f32_e32 v184, v184, v44
	v_add_f32_e32 v185, v185, v60
	v_add_f32_e32 v186, v186, v45
	v_add_f32_e32 v187, v187, v61
	v_add_f32_e32 v184, v184, v46
	v_add_f32_e32 v185, v185, v62
	v_add_f32_e32 v186, v186, v47
	v_add_f32_e32 v187, v187, v63
	v_add_f32_e32 v184, v184, v48
	v_add_f32_e32 v185, v185, v64
	v_add_f32_e32 v186, v186, v49
	v_add_f32_e32 v187, v187, v65
	v_add_f32_e32 v184, v184, v186
	v_add_f32_e32 v185, v185, v187
	v_add_f32_e32 v1, v184, v185
	v_cvt_pk_bf16_f32 v34, v34, v35
	v_cvt_pk_bf16_f32 v35, v36, v37
	v_cvt_pk_bf16_f32 v36, v38, v39
	v_cvt_pk_bf16_f32 v37, v40, v41
	v_cvt_pk_bf16_f32 v38, v42, v43
	v_cvt_pk_bf16_f32 v39, v44, v45
	v_cvt_pk_bf16_f32 v40, v46, v47
	v_cvt_pk_bf16_f32 v41, v48, v49
	v_cvt_pk_bf16_f32 v42, v50, v51
	v_cvt_pk_bf16_f32 v43, v52, v53
	v_cvt_pk_bf16_f32 v44, v54, v55
	v_cvt_pk_bf16_f32 v45, v56, v57
	v_cvt_pk_bf16_f32 v46, v58, v59
	v_cvt_pk_bf16_f32 v47, v60, v61
	v_cvt_pk_bf16_f32 v48, v62, v63
	v_cvt_pk_bf16_f32 v49, v64, v65
	v_add_f32_e32 v181, v181, v1
	s_setprio 1
	s_cmp_eq_u32 s34, 0
	s_cbranch_scc0 .Lpv_s1
	ds_read_b64 v[50:51], v194 offset:12288
	ds_read_b64 v[54:55], v194 offset:16384
	ds_read_b64 v[52:53], v195 offset:12288
	ds_read_b64 v[56:57], v195 offset:16384
	ds_read_b64 v[58:59], v196 offset:12288
	ds_read_b64 v[62:63], v196 offset:16384
	ds_read_b64 v[60:61], v197 offset:12288
	ds_read_b64 v[64:65], v197 offset:16384
	ds_read_b64 a[0:1], v198 offset:12288
	ds_read_b64 a[4:5], v198 offset:16384
	ds_read_b64 a[2:3], v199 offset:12288
	ds_read_b64 a[6:7], v199 offset:16384
	ds_read_b64 a[8:9], v200 offset:12288
	ds_read_b64 a[12:13], v200 offset:16384
	ds_read_b64 a[10:11], v201 offset:12288
	ds_read_b64 a[14:15], v201 offset:16384
	s_branch .Lpv_rd
